# prologue: second conversion range runs on the workgroups that had one item (max 2 items per workgroup)
# speedup vs baseline: 1.0020x; 1.0020x over previous
; __global__ void __launch_bounds__(512, 2) mega_fwd(Args a) {
;     ...
;         for (int it = bx; it < 2 * I_LAYER; it += G) {
;             const int l = it / I_LAYER; int r = it % I_LAYER;
;             unsigned char* wl = ws + WS_W + (size_t)l * W_LAYER;
;             if (r < I_IN) { conv_block_item(a.in[3] + (size_t)l * 1024 * 3474, nullptr, 3474, 1024, 1, a.in[2] + l * 1024, (bf16*)(wl + OW_IN), tile, r / 14, r % 14, tid); continue; } r -= I_IN;
;             if (r < I_OUT) { conv_block_item(a.in[9] + (size_t)l * 1024 * 1024, nullptr, 1024, 1024, 0, nullptr, (bf16*)(wl + OW_OUT), tile, r / 4, r % 4, tid); continue; } r -= I_OUT;
;             if (r < I_XQ) { conv_block_item(a.in[12] + (size_t)l * 1024 * 512, nullptr, 512, 1024, 0, a.in[10] + l * 1024, (bf16*)(wl + OW_XQ), tile, r / 2, r % 2, tid); continue; } r -= I_XQ;
;             if (r < I_XKV) { conv_block_item(a.in[13] + (size_t)l * 1024 * 1024, nullptr, 1024, 1024, 0, a.in[11] + l * 1024, (bf16*)(wl + OW_XKV), tile, r / 4, r % 4, tid); continue; } r -= I_XKV;
;             if (r < I_XO) { conv_block_item(a.in[14] + (size_t)l * 512 * 1024, nullptr, 1024, 512, 0, nullptr, (bf16*)(wl + OW_XO), tile, r / 4, r % 4, tid); continue; } r -= I_XO;
;             if (r < I_GU) { conv_block_item(a.in[16] + (size_t)l * 1024 * DFF, a.in[17] + (size_t)l * 1024 * DFF, DFF, 1024, 2, a.in[15] + l * 1024, (bf16*)(wl + OW_GU), tile, r / 22, r % 22, tid); continue; } r -= I_GU;
;             conv_block_item(a.in[18] + (size_t)l * DFF * 1024, nullptr, 1024, DFF, 0, nullptr, (bf16*)(wl + OW_DN), tile, r / 4, r % 4, tid);
;         }
.Lconv_after1:
	s_mov_b32 s101, 1
	s_movk_i32 s100, 0x52f
	v_readlane_b32 s2, v253, 9
	s_nop 3
	s_add_i32 s2, s2, 64
	s_and_b32 s2, s2, 0xff
	s_addk_i32 s2, 0x4f0
	s_nop 0
	v_writelane_b32 v253, s2, 9
	s_branch .Lconv_reenter
.Lconv_after2:
	v_readlane_b32 s2, v253, 9
	s_nop 3
	s_addk_i32 s2, 0xfad0
	s_and_b32 s2, s2, 0xff
	s_nop 0
	v_writelane_b32 v253, s2, 9
	s_branch .LBB0_488
